# G1 static order: column tiles 0<->2, 1<->3 swapped so gelu-epilogue tiles run on the two-unit CUs
# speedup vs baseline: 1.0656x; 1.0024x over previous
.LBB0_83:
	s_andn2_b64 vcc, exec, s[0:1]
	s_cbranch_vccnz .LBB0_310
	v_readlane_b32 s8, v252, 0
	v_readlane_b32 s9, v252, 1
	s_waitcnt lgkmcnt(0)
	s_load_dwordx2 s[22:23], s[8:9], 0xd8
	s_mul_i32 s0, s26, 0x1800000
	v_mov_b32_e32 v12, v0
	s_waitcnt lgkmcnt(0)
	s_add_u32 s0, s22, s0
	s_addc_u32 s1, s23, 0
	s_add_u32 s0, s0, 0x200000
	s_addc_u32 s1, s1, 0
	s_add_u32 s10, s22, 0x3200000
	s_addc_u32 s11, s23, 0
	s_lshl_b32 s34, s26, 17
	s_lshl_b64 s[4:5], s[34:35], 2
	s_add_u32 s4, s22, s4
	s_addc_u32 s5, s23, s5
	s_add_u32 s6, s4, 0x10000
	s_addc_u32 s7, s5, 0
	v_readlane_b32 s4, v252, 13
	v_readlane_b32 s5, v252, 14
	s_andn2_b64 vcc, exec, s[4:5]
	v_readfirstlane_b32 s28, v12
	s_cbranch_vccnz .LBB0_198
	v_lshlrev_b32_e32 v1, 4, v12
	v_add_u32_e32 v2, 0x2000, v1
	v_ashrrev_i32_e32 v4, 31, v2
	v_lshrrev_b32_e32 v4, 22, v4
	v_add_u32_e32 v4, v2, v4
	v_ashrrev_i32_e32 v13, 10, v4
	v_mul_i32_i24_e32 v4, 0x400, v13
	v_sub_u32_e32 v2, v2, v4
	v_lshrrev_b32_e32 v4, 4, v2
	v_bitop3_b32 v2, v4, v2, 32 bitop3:0x6c
	v_ashrrev_i32_e32 v4, 31, v2
	v_lshrrev_b32_e32 v4, 26, v4
	v_add_u32_e32 v4, v2, v4
	v_lshlrev_b32_e32 v5, 3, v13
	v_ashrrev_i32_e32 v14, 6, v4
	v_and_b32_e32 v5, -16, v5
	v_add_u32_e32 v5, v14, v5
	v_and_b32_e32 v6, 3, v14
	s_mov_b32 s4, 0x1fffe0
	v_lshrrev_b32_e32 v7, 2, v5
	v_lshlrev_b32_e32 v8, 1, v5
	v_and_b32_e32 v4, 0xc0, v4
	v_and_or_b32 v6, v5, s4, v6
	v_and_b32_e32 v7, 4, v7
	v_and_b32_e32 v8, 24, v8
	v_sub_u32_e32 v2, v2, v4
	v_or3_b32 v6, v6, v7, v8
	v_lshlrev_b32_e32 v7, 5, v13
	v_ashrrev_i16_sdwa v2, v217, sext(v2) dst_sel:DWORD dst_unused:UNUSED_PAD src0_sel:DWORD src1_sel:BYTE_0
	v_and_b32_e32 v7, 32, v7
	v_bfe_i32 v15, v2, 0, 16
	v_add_lshl_u32 v2, v7, v15, 1
	v_lshl_add_u32 v176, v6, 11, v2
	v_lshl_add_u32 v178, v5, 11, v2
	v_bfe_i32 v2, v12, 27, 1
	v_lshrrev_b32_e32 v2, 22, v2
	v_add_u32_e32 v2, v1, v2
	v_and_b32_e32 v2, 0xfffffc00, v2
	v_sub_u32_e32 v1, v1, v2
	v_lshrrev_b32_e32 v2, 4, v1
	v_ashrrev_i32_e32 v4, 31, v12
	v_bitop3_b32 v1, v2, v1, 32 bitop3:0x6c
	v_lshrrev_b32_e32 v4, 26, v4
	v_ashrrev_i32_e32 v2, 31, v1
	v_add_u32_e32 v4, v12, v4
	v_lshrrev_b32_e32 v2, 26, v2
	v_ashrrev_i32_e32 v17, 6, v4
	v_add_u32_e32 v2, v1, v2
	v_lshlrev_b32_e32 v4, 3, v17
	v_ashrrev_i32_e32 v16, 6, v2
	v_and_b32_e32 v4, -16, v4
	v_add_u32_e32 v4, v16, v4
	v_and_b32_e32 v5, 3, v16
	v_lshrrev_b32_e32 v6, 2, v4
	v_lshlrev_b32_e32 v7, 1, v4
	v_and_b32_e32 v2, 0xc0, v2
	s_ashr_i32 s30, s28, 6
	v_and_or_b32 v5, v4, s4, v5
	v_and_b32_e32 v6, 4, v6
	v_and_b32_e32 v7, 24, v7
	v_sub_u32_e32 v1, v1, v2
	s_ashr_i32 s29, s28, 8
	s_lshl_b32 s14, s30, 10
	v_or3_b32 v5, v5, v6, v7
	v_lshlrev_b32_e32 v6, 5, v17
	v_ashrrev_i16_sdwa v1, v217, sext(v1) dst_sel:DWORD dst_unused:UNUSED_PAD src0_sel:DWORD src1_sel:BYTE_0
	v_readlane_b32 s4, v254, 18
	v_and_b32_e32 v6, 32, v6
	v_bfe_i32 v18, v1, 0, 16
	s_nop 3
	s_cmp_lt_u32 s4, 4
	s_cselect_b32 s5, 2, 0
	s_xor_b32 s4, s4, s5
	s_lshl_b32 s4, s4, 19
	s_mov_b32 s5, 0
	s_add_u32 s18, s0, s4
	v_add_lshl_u32 v1, v6, v18, 1
	s_addc_u32 s19, s1, s5
	s_add_i32 s15, s14, 0
	v_lshl_add_u32 v2, v5, 11, v1
	s_add_i32 m0, s15, 0x10000
	v_lshl_add_u32 v180, v4, 11, v1
	global_load_lds_dwordx4 v2, s[18:19]
	s_add_i32 m0, s15, 0x12000
	s_add_u32 s4, s18, 0x40000
	global_load_lds_dwordx4 v176, s[18:19]
	s_addc_u32 s5, s19, 0
	s_add_i32 m0, s15, 0x14000
	s_load_dwordx4 s[48:51], s[8:9], 0x70
	global_load_lds_dwordx4 v2, s[4:5]
	s_add_i32 m0, s15, 0x16000
	v_mov_b32_e32 v177, v3
	global_load_lds_dwordx4 v176, s[4:5]
	v_readlane_b32 s4, v254, 32
	v_readlane_b32 s5, v254, 33
	s_add_u32 s4, s10, s4
	s_addc_u32 s5, s11, s5
	s_add_i32 s58, s15, 0x2000
	s_mov_b32 m0, s15
	s_add_u32 s24, s4, 0x40000
	global_load_lds_dwordx4 v180, s[4:5]
	s_mov_b32 m0, s58
	s_addc_u32 s25, s5, 0
	s_add_i32 s59, s15, 0x4000
	global_load_lds_dwordx4 v178, s[4:5]
	s_mov_b32 m0, s59
	s_add_i32 s60, s15, 0x6000
	global_load_lds_dwordx4 v180, s[24:25]
	s_mov_b32 m0, s60
	v_mov_b32_e32 v181, v3
	global_load_lds_dwordx4 v178, s[24:25]
	v_mov_b32_e32 v179, v3
	s_cmp_eq_u32 s29, 1
	s_mov_b32 s72, s26
	v_lshl_add_u64 v[10:11], s[18:19], 0, v[2:3]
	v_lshl_add_u64 v[8:9], s[18:19], 0, v[176:177]
	v_lshl_add_u64 v[4:5], s[4:5], 0, v[180:181]
	s_cselect_b64 s[24:25], -1, 0
	s_cmp_lg_u32 s29, 1
	v_lshl_add_u64 v[6:7], s[4:5], 0, v[178:179]
	s_cbranch_scc1 .LBB0_87
	s_barrier
.LBB0_87:
	s_add_u32 s26, s22, 0x6b00000
	s_addc_u32 s27, s23, 0
	s_lshl_b32 s30, s30, 5
	s_and_b32 s41, s30, 0x60
	s_add_i32 m0, s15, 0x18000
	v_lshl_add_u64 v[10:11], v[10:11], 0, s[16:17]
	s_lshl_b32 s34, s72, 5
	s_lshl_b32 s40, s29, 13
	s_lshl_b32 s42, s41, 7
	s_waitcnt vmcnt(2)
	s_barrier
	global_load_lds_dwordx4 v[10:11], off
	v_lshl_add_u64 v[8:9], v[8:9], 0, s[16:17]
	s_add_i32 m0, s15, 0x1a000
	s_add_i32 s61, s15, 0x8000
	s_add_i32 s62, s15, 0xa000
	global_load_lds_dwordx4 v[8:9], off
	v_lshl_add_u64 v[4:5], v[4:5], 0, s[16:17]
	s_mov_b32 m0, s61
	s_add_u32 s30, s18, 0x40080
	global_load_lds_dwordx4 v[4:5], off
	v_lshl_add_u64 v[4:5], v[6:7], 0, s[16:17]
	s_mov_b32 m0, s62
	s_addc_u32 s31, s19, 0
	global_load_lds_dwordx4 v[4:5], off
	s_add_i32 m0, s15, 0x1c000
	v_lshl_add_u64 v[4:5], s[30:31], 0, v[2:3]
	global_load_lds_dwordx4 v[4:5], off
	v_lshl_add_u64 v[4:5], s[30:31], 0, v[176:177]
	s_add_i32 m0, s15, 0x1e000
	s_cmpk_lt_u32 s28, 0x100
	global_load_lds_dwordx4 v[4:5], off
	v_lshrrev_b32_e32 v4, 1, v12
	v_and_b32_e32 v4, 24, v4
	v_and_b32_e32 v5, 15, v12
	v_lshlrev_b32_e32 v6, 1, v4
	v_lshl_or_b32 v1, s29, 6, v5
	v_lshl_or_b32 v5, v5, 6, v6
	v_lshlrev_b32_e32 v6, 2, v12
	v_and_b32_e32 v6, 32, v6
	v_bitop3_b32 v7, v5, s40, v6 bitop3:0xde
	v_bitop3_b32 v233, v5, s42, v6 bitop3:0xde
	v_lshlrev_b32_e32 v5, 14, v17
	v_and_b32_e32 v5, 0xffff8000, v5
	v_lshl_add_u32 v5, v16, 11, v5
	v_and_b32_e32 v6, 1, v17
	v_lshl_or_b32 v5, v6, 6, v5
	v_lshl_add_u32 v182, v18, 1, v5
	v_lshlrev_b32_e32 v5, 14, v13
	v_and_b32_e32 v5, 0xffff8000, v5
	s_waitcnt vmcnt(6)
	v_lshl_add_u32 v5, v14, 11, v5
	v_and_b32_e32 v6, 1, v13
	v_or_b32_e32 v234, s41, v4
	v_lshl_or_b32 v5, v6, 6, v5
	v_readlane_b32 s40, v254, 30
	s_cselect_b64 s[28:29], -1, 0
	v_mov_b32_e32 v183, v3
	v_lshl_add_u32 v184, v15, 1, v5
	v_mov_b32_e32 v185, v3
	s_mov_b32 s63, 0
	s_mov_b32 s73, -1
	v_add_u32_e32 v235, 0, v7
	s_lshl_b64 s[30:31], s[34:35], 2
	v_lshlrev_b32_e32 v236, 2, v4
	v_readlane_b32 s34, v254, 18
	s_mov_b32 s44, s40
	s_nop 3
	s_cmp_lt_u32 s34, 4
	s_cselect_b32 s75, 2, 0
	s_xor_b32 s34, s34, s75
	s_barrier
	v_readlane_b32 s41, v254, 31
	s_branch .LBB0_90

.LBB0_90:
	s_add_i32 s63, s63, 1
	v_readlane_b32 s40, v252, 16
	v_readlane_b32 s42, v252, 4
	s_mul_i32 s40, s63, s40
	s_mul_hi_u32 s41, s63, s42
	s_add_i32 s41, s41, s40
	s_mul_i32 s40, s63, s42
	v_readlane_b32 s42, v252, 5
	s_add_u32 s42, s40, s42
	v_readlane_b32 s40, v252, 15
	s_addc_u32 s43, s41, s40
	v_mov_b64_e32 v[4:5], 0x240
	v_cmp_lt_i64_e64 s[40:41], s[42:43], v[4:5]
	v_mov_b64_e32 v[4:5], 0x23f
	v_cmp_gt_i64_e32 vcc, s[42:43], v[4:5]
	s_cbranch_vccnz .LBB0_92
	s_ashr_i32 s43, s42, 31
	s_lshr_b32 s43, s43, 29
	s_add_i32 s43, s42, s43
	s_ashr_i32 s45, s43, 3
	s_and_b32 s43, s43, -8
	s_sub_i32 s42, s42, s43
	s_cmp_lt_i32 s42, 0
	s_movk_i32 s43, 0x49
	s_cselect_b32 s43, s43, 0x48
	s_mul_i32 s42, s42, s43
	s_add_i32 s42, s42, s45
	s_mul_hi_i32 s43, s42, 0x38e38e39
	s_lshr_b32 s45, s43, 31
	s_ashr_i32 s43, s43, 4
	s_add_i32 s43, s43, s45
	s_lshl_b32 s45, s43, 3
	s_sub_i32 s46, 64, s45
	s_min_i32 s47, s46, 8
	s_abs_i32 s46, s47
	v_cvt_f32_u32_e32 v4, s46
	s_sub_i32 s53, 0, s46
	s_mulk_i32 s43, 0x48
	s_sub_i32 s42, s42, s43
	v_rcp_iflag_f32_e32 v4, v4
	s_abs_i32 s43, s42
	s_xor_b32 s52, s42, s47
	s_ashr_i32 s52, s52, 31
	v_mul_f32_e32 v4, 0x4f7ffffe, v4
	v_cvt_u32_f32_e32 v4, v4
	s_nop 0
	v_readfirstlane_b32 s54, v4
	s_mul_i32 s53, s53, s54
	s_mul_hi_u32 s53, s54, s53
	s_add_i32 s54, s54, s53
	s_mul_hi_u32 s53, s43, s54
	s_mul_i32 s54, s53, s46
	s_sub_i32 s43, s43, s54
	s_add_i32 s55, s53, 1
	s_sub_i32 s54, s43, s46
	s_cmp_ge_u32 s43, s46
	s_cselect_b32 s53, s55, s53
	s_cselect_b32 s43, s54, s43
	s_add_i32 s54, s53, 1
	s_cmp_ge_u32 s43, s46
	s_cselect_b32 s43, s54, s53
	s_xor_b32 s43, s43, s52
	s_sub_i32 s46, s43, s52
	s_mul_i32 s43, s46, s47
	s_sub_i32 s42, s42, s43
	s_add_i32 s52, s45, s42
	s_cmp_lt_u32 s46, 4
	s_cselect_b32 s43, 2, 0
	s_xor_b32 s46, s46, s43
